# LRU: s_setprio 1 for the conv/carry segments (C+A), 0 for the gate segment (B), so the VALU-dense half wins arbitration while the MFMA/transcendental half fills gaps
# speedup vs baseline: 1.0119x; 1.0089x over previous
; #define LAS __attribute__((address_space(3)))
; __device__ __forceinline__ int opaque_tid() { int t = threadIdx.x; asm volatile("" : "+v"(t)); return t; }
; #define LDS_BARRIER() do { asm volatile("s_waitcnt lgkmcnt(0)" ::: "memory"); __builtin_amdgcn_s_barrier(); asm volatile("" ::: "memory"); } while (0)
; __device__ __forceinline__ void lru_strip(LAS unsigned char* lds, const Params& P, int strip, bool dry) {
;     const int tid = opaque_tid();
;     const int b = strip >> 5, h = (strip >> 2) & 7, q = strip & 3;
;     LAS float* CWL = (LAS float*)(lds + 256 * XC_PITCH + 2048 + 64 * XC_PITCH);
;     for (int i = tid; i < 640; i += NTHREADS) { const int k = i >> 7, c = i & 127; CWL[i] = k < 4 ? P.conv_w[k * 1024 + h * 128 + c] : P.conv_b[h * 128 + c]; }
;     LDS_BARRIER();
;     lru_pass<0>(lds, P, b, h, q, dry);
.LBB0_277:
	s_setprio 0
	s_cmp_lg_u32 s101, 0
	s_cbranch_scc1 .Lpp_b_noy
	s_barrier

; #define LAS __attribute__((address_space(3)))
; #define LDS_BARRIER() do { asm volatile("s_waitcnt lgkmcnt(0)" ::: "memory"); __builtin_amdgcn_s_barrier(); asm volatile("" ::: "memory"); } while (0)
; template <int dir>
; __device__ __forceinline__ void lru_pass(LAS unsigned char* lds, const Params& P, int b, int h, int q, bool dry) {
;     ...
;             LDS_BARRIER();
;             if (sc >= 2) {
;                 if (dir == 0) {
; #pragma unroll
;                     for (int i = 0; i < 4; ++i) { const int id = tid + i * NTHREADS; *(u32x4*)(Hg + (size_t)(t0_prev + (id >> 3)) * DM + (id & 7) * 4) = *(const LAS u32x4*)(TOUT + (id >> 3) * IO_WP + (id & 7) * 16); }
.LBB0_295:
	s_waitcnt lgkmcnt(0)
	s_barrier
	s_setprio 0
	s_cmp_lt_u32 s93, 2
	s_cbranch_scc1 .LBB0_297
	v_add_u32_e32 v48, v129, v149
	ds_read_b128 v[32:35], v48
	v_add_u32_e32 v48, v129, v146
	ds_read_b128 v[36:39], v48
	v_add_u32_e32 v48, v129, v144
	ds_read_b128 v[40:43], v48
	v_add_u32_e32 v48, v129, v142
	ds_read_b128 v[44:47], v48
	v_add_u32_e32 v48, s91, v148
	v_ashrrev_i32_e32 v49, 31, v48
	v_lshlrev_b64 v[48:49], 12, v[48:49]
	v_lshl_add_u64 v[48:49], v[130:131], 0, v[48:49]
	v_add_u32_e32 v50, s91, v145
	v_ashrrev_i32_e32 v51, 31, v50
	v_lshlrev_b64 v[50:51], 12, v[50:51]
	v_lshl_add_u64 v[50:51], v[130:131], 0, v[50:51]
	v_add_u32_e32 v52, s91, v143
	v_ashrrev_i32_e32 v53, 31, v52
	v_lshlrev_b64 v[52:53], 12, v[52:53]
	v_lshl_add_u64 v[52:53], v[130:131], 0, v[52:53]
	v_add_u32_e32 v54, s91, v141
	v_ashrrev_i32_e32 v55, 31, v54
	v_lshlrev_b64 v[54:55], 12, v[54:55]
	v_lshl_add_u64 v[54:55], v[130:131], 0, v[54:55]
	s_waitcnt lgkmcnt(3)
	global_store_dwordx4 v[48:49], v[32:35], off
	s_waitcnt lgkmcnt(2)
	global_store_dwordx4 v[50:51], v[36:39], off
	s_waitcnt lgkmcnt(1)
	global_store_dwordx4 v[52:53], v[40:43], off
	s_waitcnt lgkmcnt(0)
	global_store_dwordx4 v[54:55], v[44:47], off

; #define LAS __attribute__((address_space(3)))
; __device__ __forceinline__ unsigned cvt_pk_bf16(float lo, float hi) { unsigned r; asm volatile("v_cvt_pk_bf16_f32 %0, %1, %2" : "=v"(r) : "v"(lo), "v"(hi)); return r; }
; __device__ __forceinline__ float bf_lo(unsigned u) { return __uint_as_float(u << 16); }
; __device__ __forceinline__ float bf_hi(unsigned u) { return __uint_as_float(u & 0xffff0000u); }
; __device__ __forceinline__ bf16_t f2bf(float f) { return (bf16_t)(cvt_pk_bf16(f, 0.f) & 0xffffu); }
; #define LDS_BARRIER() do { asm volatile("s_waitcnt lgkmcnt(0)" ::: "memory"); __builtin_amdgcn_s_barrier(); asm volatile("" ::: "memory"); } while (0)
; template <int dir>
; __device__ __forceinline__ void lru_pass(LAS unsigned char* lds, const Params& P, int b, int h, int q, bool dry) {
;     ...
;             LDS_BARRIER();
;             float cin = carry, cend = carry;
; #pragma unroll
;             for (int w = 0; w < 8; ++w) { const float pw = AGG[(w * 2 + 0) * 32 + nl], ew = AGG[(w * 2 + 1) * 32 + nl]; if (w == wid) cin = cend; cend = fmaf(pw, cend, ew); }
;             carry = cend;
;             if (g) cin = fmaf(P0, cin, E0);
;             if (!isctx) {
; #pragma unroll
;                 for (int v = 0; v < 16; ++v) { const float hv = fmaf(zi[v], cin, zr[v]);
;                     const int s = sbase + v; const int tl = dir == 0 ? s : 255 - s;
;                     if (dir == 0) *(LAS unsigned*)(TOUT + tl * IO_WP + nl * 4) = (cvt_pk_bf16(hv, 0.f) & 0xffffu) | (pk[v] << 16);
;                     else *(LAS bf16_t*)(TOUT + tl * IO_NP + nl * 2) = f2bf((bf_lo(pk[v]) + hv) * bf_hi(pk[v])); }
.LBB0_299:
	s_or_b64 exec, exec, s[18:19]
	s_waitcnt lgkmcnt(0)
	s_barrier
	s_setprio 1
	v_add_u32_e32 v34, s99, v140
	ds_read2_b32 v[36:37], v34 offset1:32
	ds_read2_b32 v[38:39], v34 offset0:64 offset1:96
	ds_read2_b32 v[40:41], v34 offset0:128 offset1:160
	ds_read2_b32 v[42:43], v34 offset0:192 offset1:224
	v_add_u32_e32 v32, s100, v140
	ds_read2_b32 v[44:45], v32 offset1:32
	s_waitcnt lgkmcnt(4)
	v_fmac_f32_e32 v37, v36, v165
	ds_read2_b32 v[46:47], v32 offset0:64 offset1:96
	s_waitcnt lgkmcnt(4)
	v_fmac_f32_e32 v39, v38, v37
	ds_read2_b32 v[34:35], v32 offset0:128 offset1:160
	s_waitcnt lgkmcnt(4)
	v_fmac_f32_e32 v41, v40, v39
	ds_read2_b32 v[32:33], v32 offset0:192 offset1:224
	s_waitcnt lgkmcnt(4)
	v_fmac_f32_e32 v43, v42, v41
	s_waitcnt lgkmcnt(3)
	v_fmac_f32_e32 v45, v44, v43
	s_waitcnt lgkmcnt(2)
	v_fmac_f32_e32 v47, v46, v45
	s_cmp_eq_u32 s80, 0
	s_waitcnt lgkmcnt(1)
	v_fmac_f32_e32 v35, v34, v47
	s_cbranch_scc1 .LBB0_301
	v_cndmask_b32_e64 v37, v165, v37, s[14:15]
	v_cndmask_b32_e64 v37, v37, v39, s[12:13]
	v_cndmask_b32_e64 v37, v37, v41, s[10:11]
	v_cndmask_b32_e64 v37, v37, v43, s[8:9]
	v_cndmask_b32_e64 v37, v37, v45, s[4:5]
	v_cndmask_b32_e64 v37, v37, v47, s[16:17]
	v_cndmask_b32_e32 v34, v188, v187, vcc
	v_cndmask_b32_e32 v36, v189, v185, vcc
	v_cndmask_b32_e64 v37, v37, v35, s[0:1]
	v_fmac_f32_e32 v36, v34, v37
	v_cndmask_b32_e32 v34, v36, v37, vcc
	v_fmac_f32_e32 v49, v171, v34
	v_cvt_pk_bf16_f32 v36, v49, v65
	v_lshlrev_b32_e32 v37, 16, v127
	v_and_or_b32 v36, v36, s31, v37
	ds_write_b32 v164, v36
	v_fmac_f32_e32 v172, v50, v34
	v_cvt_pk_bf16_f32 v36, v172, v65
	v_lshlrev_b32_e32 v37, 16, v124
	v_and_or_b32 v36, v36, s31, v37
	ds_write_b32 v164, v36 offset:144
	v_fmac_f32_e32 v173, v51, v34
	v_cvt_pk_bf16_f32 v36, v173, v65
	v_lshlrev_b32_e32 v37, 16, v121
	v_and_or_b32 v36, v36, s31, v37
	ds_write_b32 v164, v36 offset:288
	v_fmac_f32_e32 v174, v52, v34
	v_cvt_pk_bf16_f32 v36, v174, v65
	v_lshlrev_b32_e32 v37, 16, v66
	v_and_or_b32 v36, v36, s31, v37
	ds_write_b32 v164, v36 offset:432
	v_fmac_f32_e32 v175, v53, v34
	v_cvt_pk_bf16_f32 v36, v175, v65
	v_lshlrev_b32_e32 v37, 16, v64
	v_and_or_b32 v36, v36, s31, v37
	ds_write_b32 v164, v36 offset:576
	v_fmac_f32_e32 v176, v54, v34
	v_cvt_pk_bf16_f32 v36, v176, v65
	v_lshlrev_b32_e32 v37, 16, v126
	v_and_or_b32 v36, v36, s31, v37
	ds_write_b32 v164, v36 offset:720
	v_fmac_f32_e32 v177, v55, v34
	v_cvt_pk_bf16_f32 v36, v177, v65
	v_lshlrev_b32_e32 v37, 16, v123
	v_and_or_b32 v36, v36, s31, v37
	ds_write_b32 v164, v36 offset:864
	v_fmac_f32_e32 v178, v56, v34
	v_cvt_pk_bf16_f32 v36, v178, v65
	v_lshlrev_b32_e32 v37, 16, v120
	v_and_or_b32 v36, v36, s31, v37
	ds_write_b32 v164, v36 offset:1008
	v_fmac_f32_e32 v179, v57, v34
	v_cvt_pk_bf16_f32 v36, v179, v65
	v_lshlrev_b32_e32 v37, 16, v170
	v_and_or_b32 v36, v36, s31, v37
	ds_write_b32 v164, v36 offset:1152
	v_fmac_f32_e32 v180, v58, v34
	v_cvt_pk_bf16_f32 v36, v180, v65
	v_lshlrev_b32_e32 v37, 16, v169
	v_and_or_b32 v36, v36, s31, v37
	ds_write_b32 v164, v36 offset:1296
	v_fmac_f32_e32 v181, v59, v34
	v_cvt_pk_bf16_f32 v36, v181, v65
	v_lshlrev_b32_e32 v37, 16, v168
	v_and_or_b32 v36, v36, s31, v37
	ds_write_b32 v164, v36 offset:1440
	v_fmac_f32_e32 v182, v60, v34
	v_cvt_pk_bf16_f32 v36, v182, v65
	v_lshlrev_b32_e32 v37, 16, v166
	v_and_or_b32 v36, v36, s31, v37
	ds_write_b32 v164, v36 offset:1584
	v_fmac_f32_e32 v183, v61, v34
	v_cvt_pk_bf16_f32 v36, v183, v65
	v_lshlrev_b32_e32 v37, 16, v125
	v_and_or_b32 v36, v36, s31, v37
	ds_write_b32 v164, v36 offset:1728
	v_fmac_f32_e32 v184, v62, v34
	v_cvt_pk_bf16_f32 v36, v184, v65
	v_lshlrev_b32_e32 v37, 16, v122
	v_and_or_b32 v36, v36, s31, v37
	ds_write_b32 v164, v36 offset:1872
	v_fmac_f32_e32 v63, v186, v34
	v_cvt_pk_bf16_f32 v36, v63, v65
	v_lshlrev_b32_e32 v37, 16, v67
	v_and_or_b32 v36, v36, s31, v37
	ds_write_b32 v164, v36 offset:2016
	v_fmac_f32_e32 v185, v187, v34
	v_cvt_pk_bf16_f32 v34, v185, v65
	v_lshlrev_b32_e32 v36, 16, v48
	v_and_or_b32 v34, v34, s31, v36
	ds_write_b32 v164, v34 offset:2160

; #define LAS __attribute__((address_space(3)))
; template <int dir>
; __device__ __forceinline__ void lru_pass(LAS unsigned char* lds, const Params& P, int b, int h, int q, bool dry) {
;     ...
;                 } else if (!dry) {
; #pragma unroll
;                     for (int i = 0; i < 2; ++i) { const int id = tid + i * NTHREADS; *(u32x4*)(Z + ZSLAB(8 + h, (size_t)b * SEQ + t0_prev + (id >> 2)) + q * 32 + (id & 3) * 8) = *(const LAS u32x4*)(TOUT + (id >> 2) * IO_NP + (id & 3) * 16); }
;                 }
.LBB0_309:
	s_waitcnt lgkmcnt(0)
	s_barrier
	s_setprio 0
	s_cmp_lt_u32 s46, 2
	s_cbranch_scc1 .LBB0_311
	s_ashr_i32 s7, s78, 31
	s_add_u32 s6, s26, s78
	s_addc_u32 s7, s27, s7
	v_add_u32_e32 v32, v158, v164
	ds_read_b128 v[32:35], v32
	v_lshl_add_u64 v[36:37], s[6:7], 0, v[140:141]
	v_lshlrev_b64 v[36:37], 8, v[36:37]
	v_lshl_add_u64 v[40:41], v[136:137], 0, v[36:37]
	v_add_u32_e32 v36, v158, v152
	ds_read_b128 v[36:39], v36
	s_waitcnt lgkmcnt(1)
	global_store_dwordx4 v[40:41], v[32:35], off
	s_nop 1
	v_lshl_add_u64 v[32:33], s[6:7], 0, v[138:139]
	v_lshlrev_b64 v[32:33], 8, v[32:33]
	v_lshl_add_u64 v[32:33], v[136:137], 0, v[32:33]
	s_waitcnt lgkmcnt(0)
	global_store_dwordx4 v[32:33], v[36:39], off

; #define LAS __attribute__((address_space(3)))
; __device__ __forceinline__ unsigned cvt_pk_bf16(float lo, float hi) { unsigned r; asm volatile("v_cvt_pk_bf16_f32 %0, %1, %2" : "=v"(r) : "v"(lo), "v"(hi)); return r; }
; __device__ __forceinline__ float bf_lo(unsigned u) { return __uint_as_float(u << 16); }
; __device__ __forceinline__ float bf_hi(unsigned u) { return __uint_as_float(u & 0xffff0000u); }
; __device__ __forceinline__ bf16_t f2bf(float f) { return (bf16_t)(cvt_pk_bf16(f, 0.f) & 0xffffu); }
; #define LDS_BARRIER() do { asm volatile("s_waitcnt lgkmcnt(0)" ::: "memory"); __builtin_amdgcn_s_barrier(); asm volatile("" ::: "memory"); } while (0)
; template <int dir>
; __device__ __forceinline__ void lru_pass(LAS unsigned char* lds, const Params& P, int b, int h, int q, bool dry) {
;     ...
;             LDS_BARRIER();
;             float cin = carry, cend = carry;
; #pragma unroll
;             for (int w = 0; w < 8; ++w) { const float pw = AGG[(w * 2 + 0) * 32 + nl], ew = AGG[(w * 2 + 1) * 32 + nl]; if (w == wid) cin = cend; cend = fmaf(pw, cend, ew); }
;             carry = cend;
;             if (g) cin = fmaf(P0, cin, E0);
;             if (!isctx) {
; #pragma unroll
;                 for (int v = 0; v < 16; ++v) { const float hv = fmaf(zi[v], cin, zr[v]);
;                     const int s = sbase + v; const int tl = dir == 0 ? s : 255 - s;
;                     if (dir == 0) *(LAS unsigned*)(TOUT + tl * IO_WP + nl * 4) = (cvt_pk_bf16(hv, 0.f) & 0xffffu) | (pk[v] << 16);
;                     else *(LAS bf16_t*)(TOUT + tl * IO_NP + nl * 2) = f2bf((bf_lo(pk[v]) + hv) * bf_hi(pk[v])); }
.LBB0_313:
	s_or_b64 exec, exec, s[18:19]
	s_waitcnt lgkmcnt(0)
	s_barrier
	s_setprio 1
	v_add_u32_e32 v34, s99, v161
	ds_read2_b32 v[36:37], v34 offset1:32
	ds_read2_b32 v[38:39], v34 offset0:64 offset1:96
	ds_read2_b32 v[40:41], v34 offset0:128 offset1:160
	ds_read2_b32 v[42:43], v34 offset0:192 offset1:224
	v_add_u32_e32 v32, s100, v161
	s_waitcnt lgkmcnt(3)
	v_fmac_f32_e32 v37, v36, v222
	s_waitcnt lgkmcnt(2)
	v_fmac_f32_e32 v39, v38, v37
	s_waitcnt lgkmcnt(1)
	v_fmac_f32_e32 v41, v40, v39
	ds_read2_b32 v[44:45], v32 offset1:32
	ds_read2_b32 v[46:47], v32 offset0:64 offset1:96
	ds_read2_b32 v[34:35], v32 offset0:128 offset1:160
	ds_read2_b32 v[32:33], v32 offset0:192 offset1:224
	s_waitcnt lgkmcnt(4)
	v_fmac_f32_e32 v43, v42, v41
	s_waitcnt lgkmcnt(3)
	v_fmac_f32_e32 v45, v44, v43
	s_waitcnt lgkmcnt(2)
	v_fmac_f32_e32 v47, v46, v45
	s_cmp_eq_u32 s44, 0
	s_waitcnt lgkmcnt(1)
	v_fmac_f32_e32 v35, v34, v47
	s_cbranch_scc1 .LBB0_315
	v_cndmask_b32_e64 v37, v222, v37, s[14:15]
	v_cndmask_b32_e64 v37, v37, v39, s[12:13]
	v_cndmask_b32_e64 v37, v37, v41, s[10:11]
	v_cndmask_b32_e64 v37, v37, v43, s[8:9]
	v_cndmask_b32_e64 v37, v37, v45, s[4:5]
	v_cndmask_b32_e64 v37, v37, v47, s[16:17]
	v_cndmask_b32_e32 v34, v244, v242, vcc
	v_cndmask_b32_e32 v36, v245, v241, vcc
	v_cndmask_b32_e64 v37, v37, v35, s[0:1]
	v_fmac_f32_e32 v36, v34, v37
	v_cndmask_b32_e32 v34, v36, v37, vcc
	v_fmac_f32_e32 v49, v227, v34
	v_lshlrev_b32_e32 v36, 16, v226
	v_add_f32_e32 v36, v49, v36
	v_and_b32_e32 v37, 0xffff0000, v226
	v_mul_f32_e32 v36, v36, v37
	v_cvt_pk_bf16_f32 v36, v36, v65
	ds_write_b16 v206, v36
	v_fmac_f32_e32 v228, v50, v34
	v_lshlrev_b32_e32 v36, 16, v225
	v_add_f32_e32 v36, v228, v36
	v_and_b32_e32 v37, 0xffff0000, v225
	v_mul_f32_e32 v36, v36, v37
	v_cvt_pk_bf16_f32 v36, v36, v65
	ds_write_b16 v207, v36
	v_fmac_f32_e32 v229, v51, v34
	v_lshlrev_b32_e32 v36, 16, v224
	v_add_f32_e32 v36, v229, v36
	v_and_b32_e32 v37, 0xffff0000, v224
	v_mul_f32_e32 v36, v36, v37
	v_cvt_pk_bf16_f32 v36, v36, v65
	ds_write_b16 v208, v36
	v_fmac_f32_e32 v230, v52, v34
	v_lshlrev_b32_e32 v36, 16, v223
	v_add_f32_e32 v36, v230, v36
	v_and_b32_e32 v37, 0xffff0000, v223
	v_mul_f32_e32 v36, v36, v37
	v_cvt_pk_bf16_f32 v36, v36, v65
	ds_write_b16 v209, v36
	v_fmac_f32_e32 v231, v53, v34
	v_lshlrev_b32_e32 v36, 16, v135
	v_add_f32_e32 v36, v231, v36
	v_and_b32_e32 v37, 0xffff0000, v135
	v_mul_f32_e32 v36, v36, v37
	v_cvt_pk_bf16_f32 v36, v36, v65
	ds_write_b16 v210, v36
	v_fmac_f32_e32 v232, v54, v34
	v_lshlrev_b32_e32 v36, 16, v134
	v_add_f32_e32 v36, v232, v36
	v_and_b32_e32 v37, 0xffff0000, v134
	v_mul_f32_e32 v36, v36, v37
	v_cvt_pk_bf16_f32 v36, v36, v65
	ds_write_b16 v211, v36
	v_fmac_f32_e32 v233, v55, v34
	v_lshlrev_b32_e32 v36, 16, v133
	v_add_f32_e32 v36, v233, v36
	v_and_b32_e32 v37, 0xffff0000, v133
	v_mul_f32_e32 v36, v36, v37
	v_cvt_pk_bf16_f32 v36, v36, v65
	ds_write_b16 v212, v36
	v_fmac_f32_e32 v234, v56, v34
	v_lshlrev_b32_e32 v36, 16, v131
	v_add_f32_e32 v36, v234, v36
	v_and_b32_e32 v37, 0xffff0000, v131
	v_mul_f32_e32 v36, v36, v37
	v_cvt_pk_bf16_f32 v36, v36, v65
	ds_write_b16 v213, v36
	v_fmac_f32_e32 v235, v57, v34
	v_lshlrev_b32_e32 v36, 16, v132
	v_add_f32_e32 v36, v235, v36
	v_and_b32_e32 v37, 0xffff0000, v132
	v_mul_f32_e32 v36, v36, v37
	v_cvt_pk_bf16_f32 v36, v36, v65
	ds_write_b16 v214, v36
	v_fmac_f32_e32 v236, v58, v34
	v_lshlrev_b32_e32 v36, 16, v130
	v_add_f32_e32 v36, v236, v36
	v_and_b32_e32 v37, 0xffff0000, v130
	v_mul_f32_e32 v36, v36, v37
	v_cvt_pk_bf16_f32 v36, v36, v65
	ds_write_b16 v215, v36
	v_fmac_f32_e32 v237, v59, v34
	v_lshlrev_b32_e32 v36, 16, v129
	v_add_f32_e32 v36, v237, v36
	v_and_b32_e32 v37, 0xffff0000, v129
	v_mul_f32_e32 v36, v36, v37
	v_cvt_pk_bf16_f32 v36, v36, v65
	ds_write_b16 v216, v36
	v_fmac_f32_e32 v238, v60, v34
	v_lshlrev_b32_e32 v36, 16, v128
	v_add_f32_e32 v36, v238, v36
	v_and_b32_e32 v37, 0xffff0000, v128
	v_mul_f32_e32 v36, v36, v37
	v_cvt_pk_bf16_f32 v36, v36, v65
	ds_write_b16 v217, v36
	v_fmac_f32_e32 v239, v61, v34
	v_lshlrev_b32_e32 v36, 16, v67
	v_add_f32_e32 v36, v239, v36
	v_and_b32_e32 v37, 0xffff0000, v67
	v_mul_f32_e32 v36, v36, v37
	v_cvt_pk_bf16_f32 v36, v36, v65
	ds_write_b16 v218, v36
	v_fmac_f32_e32 v240, v62, v34
	v_lshlrev_b32_e32 v36, 16, v66
	v_add_f32_e32 v36, v240, v36
	v_and_b32_e32 v37, 0xffff0000, v66
	v_mul_f32_e32 v36, v36, v37
	v_cvt_pk_bf16_f32 v36, v36, v65
	ds_write_b16 v219, v36
	v_fmac_f32_e32 v63, v243, v34
	v_lshlrev_b32_e32 v36, 16, v64
	v_add_f32_e32 v36, v63, v36
	v_and_b32_e32 v37, 0xffff0000, v64
	v_mul_f32_e32 v36, v36, v37
	v_cvt_pk_bf16_f32 v36, v36, v65
	v_fmac_f32_e32 v241, v242, v34
	v_lshlrev_b32_e32 v34, 16, v48
	ds_write_b16 v220, v36
	v_add_f32_e32 v34, v241, v34
	v_and_b32_e32 v36, 0xffff0000, v48
	v_mul_f32_e32 v34, v34, v36
	v_cvt_pk_bf16_f32 v34, v34, v65
	ds_write_b16 v221, v34
